# W_in phase end: counted wait (older-than-the-16-epilogue-stores only) before the forget-gate tail, so its loads are issued while the write-through stores drain
# baseline (speedup 1.0000x reference)
; #define PG8_WAIT_V(n) asm volatile("s_waitcnt vmcnt(" #n ")" ::: "memory")
; #define PG8_BAR __builtin_amdgcn_s_barrier()
; #define LAS __attribute__((address_space(3)))
; template <class Epi, class Sched, bool ALIGN_EPI = false, bool SP2 = false>
; __device__ __forceinline__ void gemm_phase(PG8_LAS unsigned char* lds, const Gemm g, const Sched& S, const Epi& E, const int tid) {
;     ...
;     PG8_WAIT_V(0);
;     if constexpr (!ALIGN_EPI) { if (wr == 0) PG8_BAR; }
;     PG8_BAR;
; __device__ __forceinline__ void fg_tail(const Args& a, int l, LAS unsigned char* lds, const int tid) {
;     ...
;     LAS f32x4* wl = (LAS f32x4*)lds;
;     {
;         const f32x4* wsrc = (const f32x4*)((const float*)(ws + WS_WFGT) + (size_t)l * 8192);
; #pragma unroll
;         for (int i = 0; i < 4; ++i) { const int idx = tid + 512 * i, j = idx >> 8, k4 = idx & 255, ln = k4 >> 2, q = k4 & 3; wl[(j * 4 + q) * 64 + ln] = wsrc[idx]; }
;     }
;     __syncthreads();
;     const bf16_t* H = (const bf16_t*)(ws + WS_H); const float* rowss = (const float*)(ws + WS_ROWSS) + (size_t)(2 * l) * MT * 4;
;     const float* mod = (const float*)(ws + WS_MOD) + (size_t)l * 8 * MODW; float* logf = (float*)(ws + WS_LOGF);
;     const float bfv = a.in[7][l * 8 + (lane >> 3)];
;     for (int chunk = blockIdx.x * 8 + wid; chunk * 8 < MT; chunk += gridDim.x * 8) {
;         const int rowc = chunk * 8, b = rowc >> 11;
;         f32x4 sh[4];
; #pragma unroll
;         for (int q = 0; q < 4; ++q) sh[q] = *(const f32x4*)(mod + (size_t)b * MODW + 16 * lane + 4 * q);
; #pragma unroll 1
;         for (int jb = 0; jb < 8; jb += 4) {
;             f32x4 rs4v[4]; u32x4 w0v[4], w1v[4];
; #pragma unroll
;             for (int j = 0; j < 4; ++j) { const int row = rowc + jb + j; rs4v[j] = *(const f32x4*)(rowss + (size_t)row * 4); w0v[j] = *(const u32x4*)(H + (size_t)row * DM + 16 * lane); w1v[j] = *(const u32x4*)(H + (size_t)row * DM + 16 * lane + 8); }
.Lfg_direct:
	s_waitcnt vmcnt(0)
	s_branch .LBB0_480
.LBB0_479:
	s_waitcnt vmcnt(16)
	v_readlane_b32 s60, v251, 40
	v_readlane_b32 s74, v251, 54
	v_readlane_b32 s75, v251, 55
	s_mov_b32 s27, 0x12000
	s_barrier
	v_readlane_b32 s61, v251, 41
	v_readlane_b32 s62, v251, 42
	v_readlane_b32 s63, v251, 43
	v_readlane_b32 s64, v251, 44
	v_readlane_b32 s65, v251, 45
	v_readlane_b32 s66, v251, 46
	v_readlane_b32 s67, v251, 47
	v_readlane_b32 s68, v251, 48
	v_readlane_b32 s69, v251, 49
	v_readlane_b32 s70, v251, 50
	v_readlane_b32 s71, v251, 51
	v_readlane_b32 s72, v251, 52
	v_readlane_b32 s73, v251, 53
.LBB0_480:
	v_readlane_b32 s0, v252, 24
	v_lshlrev_b32_e32 v0, 10, v188
	v_lshlrev_b32_e32 v2, 2, v188
	v_ashrrev_i32_e32 v189, 31, v188
	v_readlane_b32 s1, v252, 25
	v_and_b32_e32 v0, 0xc00, v0
	v_and_b32_e32 v2, 0x3f0, v2
	s_waitcnt lgkmcnt(0)
	v_lshl_add_u64 v[190:191], v[188:189], 4, s[0:1]
	v_add3_u32 v0, 0, v0, v2
	v_and_b32_e32 v18, 0xfffff00, v188
	v_lshl_add_u32 v209, v18, 4, v0
	v_add_u32_e32 v18, 0x200, v188
	v_and_b32_e32 v18, 0xfffff00, v18
	v_lshl_add_u32 v210, v18, 4, v0
	v_add_u32_e32 v18, 0x400, v188
	v_and_b32_e32 v18, 0xfffff00, v18
	v_lshl_add_u32 v211, v18, 4, v0
	v_add_u32_e32 v18, 0x600, v188
	v_and_b32_e32 v18, 0xfffff00, v18
	v_lshl_add_u32 v213, v18, 4, v0
	v_readlane_b32 s0, v252, 26
	v_ashrrev_i32_e32 v0, 6, v188
	v_mov_b32_e32 v212, v248
	v_and_b32_e32 v208, 63, v188
	v_bfe_u32 v2, v188, 3, 3
	v_or_b32_e32 v2, s0, v2
	v_readlane_b32 s0, v249, 3
	v_ashrrev_i32_e32 v3, 31, v2
	v_lshl_add_u64 v[192:193], v[2:3], 2, s[74:75]
	v_add_u32_e32 v189, s0, v0
	s_movk_i32 s0, 0x800
	v_cmp_gt_i32_e64 s[0:1], s0, v189
	v_readlane_b32 s2, v252, 32
	v_readlane_b32 s3, v252, 33
	v_readlane_b32 s4, v249, 61
	v_readlane_b32 s5, v249, 62
	s_mov_b32 s30, 0xcccccccc
	s_mov_b32 s31, 0xcccccccc
	s_mov_b32 s40, 0xaaaaaaaa
	s_mov_b32 s41, 0xaaaaaaaa
	v_lshlrev_b32_e32 v184, 14, v189
	v_lshl_add_u32 v184, v208, 5, v184
	v_lshrrev_b32_e32 v215, 8, v189
	v_mul_u32_u24_e32 v215, 0x6000, v215
	v_lshl_add_u32 v215, v208, 6, v215
	v_and_b32_e32 v216, 7, v208
	v_lshlrev_b32_e32 v217, 7, v189
	v_lshl_add_u32 v217, v216, 4, v217
	v_lshlrev_b32_e32 v246, 8, v189
	v_lshl_add_u32 v246, v216, 5, v246
	v_lshrrev_b32_e32 v216, 3, v208
	v_lshl_add_u32 v246, v216, 2, v246
	s_mov_b64 s[6:7], 0x2000
	v_lshl_add_u64 v[18:19], v[190:191], 0, s[6:7]
	s_mov_b64 s[6:7], 0x4000
	v_lshl_add_u64 v[20:21], v[190:191], 0, s[6:7]
	s_mov_b64 s[6:7], 0x6000
	v_lshl_add_u64 v[22:23], v[190:191], 0, s[6:7]
	global_load_dwordx4 v[2:5], v[190:191], off
	global_load_dwordx4 v[6:9], v[18:19], off
	global_load_dwordx4 v[10:13], v[20:21], off
	global_load_dwordx4 v[14:17], v[22:23], off
	s_and_saveexec_b64 s[38:39], s[0:1]
	global_load_dword v214, v[192:193], off
	global_load_dwordx4 v[130:133], v215, s[2:3]
	global_load_dwordx4 v[134:137], v215, s[2:3] offset:16
	global_load_dwordx4 v[138:141], v215, s[2:3] offset:32
	global_load_dwordx4 v[142:145], v215, s[2:3] offset:48
	global_load_dwordx4 v[178:181], v217, s[34:35]
	global_load_dwordx4 v[146:149], v184, s[94:95]
	global_load_dwordx4 v[150:153], v184, s[94:95] offset:16
	global_load_dwordx4 v[154:157], v184, s[94:95] offset:2048
	global_load_dwordx4 v[158:161], v184, s[94:95] offset:2064
	v_add_u32_e32 v184, 0x1000, v184
	global_load_dwordx4 v[162:165], v184, s[94:95]
	global_load_dwordx4 v[166:169], v184, s[94:95] offset:16
	global_load_dwordx4 v[170:173], v184, s[94:95] offset:2048
	global_load_dwordx4 v[174:177], v184, s[94:95] offset:2064
	v_add_u32_e32 v184, 0x1000, v184
	s_or_b64 exec, exec, s[38:39]
	s_cmp_lg_u64 s[0:1], 0
	s_cbranch_scc1 .Lfg_wv
	s_waitcnt vmcnt(0)
	s_branch .Lfg_wd
